# v33: phase 2 keeps the cumulative log-gates in log2 units (1/16 scale constant times log2 e), so the 61 per-exponential multiplies by log2 e go away; f32 throughout
# speedup vs baseline: 1.0026x; 1.0026x over previous
; #define LAS __attribute__((address_space(3)))
; __device__ __forceinline__ int opaque_tid() { int t = threadIdx.x; asm volatile("" : "+v"(t)); return t; }
; __device__ __forceinline__ void phase_gla_pre(const Params& P, LAS unsigned char* lds, bool dry) {
;     const int tid = opaque_tid(), lane = tid & 63, w = tid >> 6, fr = lane & 15, g = lane >> 4;
;     bf16_t* PJ = (bf16_t*)(P.ws + WS_PJ); const float* LR = (const float*)(P.ws + WS_LR); float* DEC = (float*)(P.ws + WS_DEC); bf16_t* PB = (bf16_t*)(P.ws + WS_PB);
;     constexpr int QP = 272, BP = 528, O_KI = 64 * QP, O_B = 2 * 64 * QP, O_LR = O_B + 64 * BP;
;     LAS unsigned char* Lqi = lds; LAS unsigned char* Lki = lds + O_KI; LAS unsigned char* Lb = lds + O_B; LAS float* Llr = (LAS float*)(lds + O_LR);
;     const int te = tid >> 3, kc = tid & 7;
;     u32x4 rq[2], rk[2]; f32x4 rl = (f32x4){0.f, 0.f, 0.f, 0.f};
;     int item = blockIdx.x;
;     if (item < 2048) {
;         const int bh = item >> 6, row0 = (bh >> 2) * SEQ + (item & 63) * 64; const bf16_t* p_ = PJ + ((size_t)bh * SEQ + (item & 63) * 64 + te) * 128 + 16 * kc;
;         rq[0] = *(const u32x4*)(p_ + T_Q); rq[1] = *(const u32x4*)(p_ + T_Q + 8); rk[0] = *(const u32x4*)(p_ + T_K); rk[1] = *(const u32x4*)(p_ + T_K + 8);
;         if (tid < 256) rl = *(const f32x4*)(LR + (size_t)row0 * 16 + 4 * tid);
;     }
;     for (; item < 2048; item += gridDim.x) {
;         const int bh = item >> 6, c = item & 63, b = bh >> 2, h = bh & 3, row0 = b * SEQ + c * 64;
;         if (tid < 256) *(LAS f32x4*)(Llr + 4 * tid) = rl;
;         bf16x8 bhi = (bf16x8){0, 0, 0, 0, 0, 0, 0, 0}, blo = bhi;
;         if (g < 2) { f32x4 w0, w1;
; #pragma unroll
;             for (int j = 0; j < 4; ++j) { w0[j] = P.w_gate_up[(8 * g + j) * 512 + h * 128 + 16 * w + fr]; w1[j] = P.w_gate_up[(8 * g + 4 + j) * 512 + h * 128 + 16 * w + fr]; }
;             split8(w0, w1, bhi, blo); }
;         const float bg = P.b_gate_up[h * 128 + 16 * w + fr];
.LBB0_478:
	s_or_b64 exec, exec, s[6:7]
	v_mbcnt_hi_u32_b32 v30, -1, v195
	v_add_u32_e32 v31, -16, v30
	v_and_b32_e32 v32, 64, v30
	v_cmp_lt_i32_e32 vcc, v31, v32
	v_lshlrev_b32_e32 v50, 1, v21
	v_mov_b32_e32 v51, 0
	v_cndmask_b32_e32 v31, v31, v30, vcc
	v_lshlrev_b32_e32 v83, 2, v31
	v_subrev_u32_e32 v31, 32, v30
	v_ashrrev_i32_e32 v26, 6, v24
	v_and_b32_e32 v27, 15, v24
	v_cmp_lt_i32_e32 vcc, v31, v32
	v_lshl_add_u64 v[52:53], s[44:45], 0, v[50:51]
	v_lshlrev_b32_e32 v50, 2, v21
	v_ashrrev_i32_e32 v21, 7, v24
	v_lshl_or_b32 v81, v26, 4, v27
	v_cndmask_b32_e32 v30, v31, v30, vcc
	s_add_i32 s3, 0, 0x10c00
	v_lshl_add_u64 v[56:57], v[22:23], 2, s[76:77]
	v_lshlrev_b32_e32 v22, 1, v26
	v_lshl_or_b32 v26, v21, 4, v27
	v_bfe_u32 v28, v24, 4, 2
	v_lshlrev_b32_e32 v29, 4, v24
	v_lshlrev_b32_e32 v84, 2, v30
	v_or_b32_e32 v30, v32, v27
	v_lshl_add_u32 v32, v27, 6, s3
	s_movk_i32 s3, 0x210
	v_and_b32_e32 v24, 2, v22
	v_lshlrev_b32_e32 v22, 6, v26
	v_mul_lo_u32 v34, v48, s3
	v_ashrrev_i32_e32 v23, 31, v22
	s_movk_i32 s3, 0x110
	v_mov_b32_e32 v31, 0xc0
	v_lshl_add_u64 v[58:59], v[22:23], 1, s[72:73]
	v_mul_lo_u32 v22, v26, s3
	v_lshl_or_b32 v85, v30, 2, v31
	v_lshlrev_b32_e32 v30, 2, v28
	v_add_u32_e32 v35, 0, v22
	v_lshlrev_b32_e32 v22, 4, v24
	v_cmp_le_i32_e64 s[14:15], v24, v21
	v_or_b32_e32 v39, v22, v27
	v_cmp_lt_i32_e64 s[16:17], v24, v21
	v_or_b32_e32 v21, 16, v22
	v_or_b32_e32 v22, v22, v30
	v_or_b32_e32 v24, v21, v27
	v_or_b32_e32 v27, 2, v22
	v_cmp_gt_i32_e64 s[22:23], v27, v26
	v_or_b32_e32 v27, 3, v22
	v_or_b32_e32 v21, v21, v30
	v_add_u32_e32 v86, 0, v34
	v_lshlrev_b32_e32 v87, 6, v25
	v_lshlrev_b32_e32 v25, 8, v48
	v_lshlrev_b32_e32 v23, 4, v28
	v_cmp_gt_i32_e64 s[24:25], v27, v26
	v_cmp_gt_i32_e64 s[26:27], v21, v26
	v_cmp_lt_i32_e64 s[28:29], v21, v26
	v_or_b32_e32 v27, 2, v21
	v_or_b32_e32 v21, 3, v21
	v_cmp_gt_u32_e64 s[6:7], 2, v28
	v_lshlrev_b32_e32 v80, 12, v28
	v_cmp_eq_u32_e64 s[8:9], 0, v28
	v_cmp_lt_u32_e64 s[10:11], 1, v28
	v_lshl_add_u32 v31, v81, 2, 0
	v_lshlrev_b32_e32 v33, 5, v28
	v_sub_u32_e32 v25, v86, v25
	v_add_u32_e32 v34, 0, v23
	v_mul_u32_u24_e32 v28, 0x840, v28
	v_or_b32_e32 v36, 16, v87
	v_or_b32_e32 v37, 32, v87
	v_or_b32_e32 v38, 48, v87
	v_mul_u32_u24_e32 v39, 0x110, v39
	v_mul_u32_u24_e32 v24, 0x110, v24
	v_cmp_gt_i32_e64 s[34:35], v21, v26
	s_add_i32 s36, s2, s38
	v_add_u32_e32 v21, 0, v29
	s_add_i32 s94, 0, 0x109f0
	v_add_u32_e32 v82, 0x800, v81
	v_cmp_eq_u32_e64 s[12:13], 63, v48
	v_lshl_add_u64 v[54:55], s[50:51], 0, v[50:51]
	v_cmp_gt_i32_e64 s[18:19], v22, v26
	v_cmp_lt_i32_e64 s[20:21], v22, v26
	v_cmp_gt_i32_e64 s[30:31], v27, v26
	s_lshl_b32 s3, s38, 6
	s_lshl_b32 s84, s36, 4
	s_lshl_b32 s85, s38, 4
	v_add_u32_e32 v88, 0x10c00, v21
	s_movk_i32 s86, 0x7fff
	s_mov_b32 s87, 0xffff0000
	s_mov_b32 s88, 0x7060302
	s_mov_b32 s89, 0xbfb8aa3b
	s_mov_b32 s90, 0x800000
	s_mov_b32 s91, 0x3f317217
	s_mov_b32 s92, 0x7f800000
	s_mov_b32 s93, 0x3db8aa3b
	v_add_u32_e32 v89, s94, v36
	v_add_u32_e32 v90, s94, v37
	v_add_u32_e32 v91, s94, v38
	v_add_u32_e32 v92, v25, v20
	s_mov_b32 s95, 0xa000000
	s_mov_b64 s[76:77], 0x8000000
	s_mov_b64 s[78:79], 0xa000000
	v_add_u32_e32 v93, v34, v39
	v_lshlrev_b32_e32 v50, 1, v22
	v_add_u32_e32 v94, v34, v24
	v_mov_b32_e32 v95, 1
	v_add_u32_e32 v96, v32, v33
	v_mov_b32_e32 v97, 0x41b17218
	v_add_u32_e32 v98, v31, v28
	v_add_u32_e32 v99, v35, v23
	s_mov_b32 s80, s2
	s_branch .LBB0_480

; #define LAS __attribute__((address_space(3)))
; __device__ __forceinline__ void phase_gla_pre(const Params& P, LAS unsigned char* lds, bool dry) {
;     ...
;         for (int tt = 0; tt < 4; ++tt) {
;             bf16x8 ahi = (bf16x8){0, 0, 0, 0, 0, 0, 0, 0}, alo = ahi;
;             if (g < 2) { const f32x4 l0 = *(const LAS f32x4*)(Llr + (16 * tt + fr) * 16 + 8 * g), l1 = *(const LAS f32x4*)(Llr + (16 * tt + fr) * 16 + 8 * g + 4); split8(l0, l1, ahi, alo); }
;             f32x4 acc = (f32x4){bg, bg, bg, bg};
;             acc = __builtin_amdgcn_mfma_f32_16x16x32_bf16(alo, bhi, acc, 0, 0, 0); acc = __builtin_amdgcn_mfma_f32_16x16x32_bf16(ahi, blo, acc, 0, 0, 0); acc = __builtin_amdgcn_mfma_f32_16x16x32_bf16(ahi, bhi, acc, 0, 0, 0);
;             float pr[4];
; #pragma unroll
;             for (int r = 0; r < 4; ++r) { const float lg = acc[r]; const float ls = fminf(lg, 0.f) - __logf(1.0f + __expf(-fabsf(lg))); pr[r] = ls * (1.0f / 16.0f) + (r ? pr[r - 1] : 0.f); }
;             const float T = pr[3];
;             const float u1 = __shfl_up(T, 16), s1 = T + (g >= 1 ? u1 : 0.f);
;             const float u2 = __shfl_up(s1, 32), s2 = s1 + (g >= 2 ? u2 : 0.f);
;             const float base = run + (s2 - T); run += __shfl(s2, 48 + fr);
; #pragma unroll
;             for (int r = 0; r < 4; ++r) *(LAS float*)(Lb + (16 * tt + 4 * g + r) * BP + (16 * w + fr) * 4) = base + pr[r];
.Lp2_nowait1:
	v_mov_b32_e32 v140, v20
	v_mov_b32_e32 v141, v21
	v_mov_b32_e32 v142, v22
	v_mov_b32_e32 v143, v23
	v_mov_b32_e32 v144, v24
	v_mov_b32_e32 v145, v25
	v_mov_b32_e32 v146, v26
	v_mov_b32_e32 v147, v27
	v_mov_b32_e32 v148, v28
	s_and_b32 s98, s38, 0xff
	s_cselect_b32 s98, 0, 1
	v_mov_b32_e32 v29, v28
	v_mov_b32_e32 v30, v28
	v_mov_b32_e32 v31, v28
	s_nop 1
	v_mfma_f32_16x16x32_bf16 v[32:35], v[100:103], v[20:23], v[28:31]
	v_mfma_f32_16x16x32_bf16 v[32:35], v[104:107], v[24:27], v[32:35]
	v_mfma_f32_16x16x32_bf16 v[32:35], v[104:107], v[20:23], v[32:35]
	s_nop 7
	v_min_f32_e32 v36, 0, v32
	v_mul_f32_e64 v32, |v32|, s89
	v_exp_f32_e32 v32, v32
	v_mul_f32_e64 v37, |v33|, s89
	v_exp_f32_e32 v37, v37
	v_add_f32_e32 v32, 1.0, v32
	v_add_f32_e32 v37, 1.0, v37
	v_log_f32_e32 v32, v32
	v_log_f32_e32 v37, v37
	v_mul_f32_e32 v39, 0x3f317217, v32
	v_fma_f32 v39, v32, s91, -v39
	v_fmac_f32_e32 v39, 0x3377d1cf, v32
	v_fmac_f32_e32 v39, 0x3f317217, v32
	v_min_f32_e32 v33, 0, v33
	v_sub_f32_e32 v32, v36, v39
	v_mul_f32_e32 v36, 0x3f317217, v37
	v_fma_f32 v36, v37, s91, -v36
	v_fmac_f32_e32 v36, 0x3377d1cf, v37
	v_fmac_f32_e32 v36, 0x3f317217, v37
	v_fma_f32 v32, v32, s93, 0
	v_mul_f32_e64 v37, |v34|, s89
	v_exp_f32_e32 v37, v37
	v_sub_f32_e32 v33, v33, v36
	v_add_f32_e32 v36, 1.0, v37
	s_nop 1
	v_log_f32_e32 v36, v36
	v_fmamk_f32 v37, v33, 0x3db8aa3b, v32
	v_min_f32_e32 v33, 0, v34
	v_mul_f32_e32 v34, 0x3f317217, v36
	v_fma_f32 v34, v36, s91, -v34
	v_fmac_f32_e32 v34, 0x3377d1cf, v36
	v_fmac_f32_e32 v34, 0x3f317217, v36
	s_nop 0
	v_mul_f32_e64 v36, |v35|, s89
	v_exp_f32_e32 v36, v36
	v_sub_f32_e32 v33, v33, v34
	v_add_u32_e32 v38, 0x8800, v98
	v_add_f32_e32 v34, 1.0, v36
	s_nop 1
	v_log_f32_e32 v34, v34
	v_fmamk_f32 v36, v33, 0x3db8aa3b, v37
	v_min_f32_e32 v33, 0, v35
	v_mul_f32_e32 v35, 0x3f317217, v34
	v_fma_f32 v35, v34, s91, -v35
	v_fmac_f32_e32 v35, 0x3377d1cf, v34
	v_fmac_f32_e32 v35, 0x3f317217, v34
	s_nop 1
	v_sub_f32_e32 v33, v33, v35
	v_fmamk_f32 v34, v33, 0x3db8aa3b, v36
	ds_bpermute_b32 v33, v83, v34
	s_waitcnt lgkmcnt(0)
	v_cndmask_b32_e64 v33, v33, 0, s[8:9]
	v_add_f32_e32 v33, v33, v34
	ds_bpermute_b32 v35, v84, v33
	s_waitcnt lgkmcnt(0)
	v_cndmask_b32_e64 v35, 0, v35, s[10:11]
	v_add_f32_e32 v33, v35, v33
	v_sub_f32_e32 v35, v33, v34
	ds_bpermute_b32 v33, v85, v33
	v_add_f32_e32 v35, 0, v35
	v_add_f32_e32 v32, v32, v35
	v_add_f32_e32 v37, v37, v35
	ds_write2_b32 v38, v32, v37 offset1:132
	v_add_f32_e32 v32, v36, v35
	v_add_f32_e32 v34, v34, v35
	v_add_u32_e32 v35, 0x8c00, v98
	ds_write2_b32 v35, v32, v34 offset0:8 offset1:140
	v_mov_b32_e32 v108, 0
	v_mov_b32_e32 v109, 0
	v_mov_b32_e32 v110, 0
	v_mov_b32_e32 v111, 0
	v_mov_b32_e32 v112, 0
	v_mov_b32_e32 v113, 0
	v_mov_b32_e32 v114, 0
	v_mov_b32_e32 v115, 0
	s_and_saveexec_b64 s[36:37], s[6:7]
	s_cbranch_execz .LBB0_488
	ds_read_b128 v[34:37], v96 offset:1024
	ds_read_b128 v[38:41], v96 offset:1040
	s_waitcnt lgkmcnt(1)
	v_cvt_pk_bf16_f32 v112, v34, v35
	v_lshlrev_b32_e32 v132, 16, v112
	v_and_b32_e32 v133, 0xffff0000, v112
	v_pk_add_f32 v[34:35], v[34:35], v[132:133] neg_lo:[0,1] neg_hi:[0,1]
	v_cvt_pk_bf16_f32 v113, v36, v37
	v_lshlrev_b32_e32 v134, 16, v113
	v_and_b32_e32 v135, 0xffff0000, v113
	v_pk_add_f32 v[36:37], v[36:37], v[134:135] neg_lo:[0,1] neg_hi:[0,1]
	s_waitcnt lgkmcnt(0)
	v_cvt_pk_bf16_f32 v114, v38, v39
	v_lshlrev_b32_e32 v136, 16, v114
	v_and_b32_e32 v137, 0xffff0000, v114
	v_pk_add_f32 v[38:39], v[38:39], v[136:137] neg_lo:[0,1] neg_hi:[0,1]
	v_cvt_pk_bf16_f32 v115, v40, v41
	v_lshlrev_b32_e32 v138, 16, v115
	v_and_b32_e32 v139, 0xffff0000, v115
	v_pk_add_f32 v[40:41], v[40:41], v[138:139] neg_lo:[0,1] neg_hi:[0,1]
	s_nop 0
	v_cvt_pk_bf16_f32 v111, v40, v41
	v_cvt_pk_bf16_f32 v110, v38, v39
	v_cvt_pk_bf16_f32 v109, v36, v37
	v_cvt_pk_bf16_f32 v108, v34, v35
.LBB0_488:
	s_or_b64 exec, exec, s[36:37]
	s_nop 0
	v_mfma_f32_16x16x32_bf16 v[34:37], v[108:111], v[20:23], v[28:31]
	v_mfma_f32_16x16x32_bf16 v[34:37], v[112:115], v[24:27], v[34:37]
	v_mfma_f32_16x16x32_bf16 v[34:37], v[112:115], v[20:23], v[34:37]
	s_nop 7
	v_min_f32_e32 v38, 0, v34
	v_mul_f32_e64 v34, |v34|, s89
	v_exp_f32_e32 v34, v34
	v_mul_f32_e64 v39, |v35|, s89
	v_exp_f32_e32 v39, v39
	v_add_f32_e32 v34, 1.0, v34
	v_add_f32_e32 v39, 1.0, v39
	v_log_f32_e32 v34, v34
	v_log_f32_e32 v39, v39
	v_mul_f32_e32 v41, 0x3f317217, v34
	v_fma_f32 v41, v34, s91, -v41
	v_fmac_f32_e32 v41, 0x3377d1cf, v34
	v_fmac_f32_e32 v41, 0x3f317217, v34
	v_mul_f32_e32 v42, 0x3f317217, v39
	v_sub_f32_e32 v34, v38, v41
	v_fma_f32 v38, v39, s91, -v42
	v_fmac_f32_e32 v38, 0x3377d1cf, v39
	v_fmac_f32_e32 v38, 0x3f317217, v39
	v_min_f32_e32 v35, 0, v35
	v_mul_f32_e64 v39, |v36|, s89
	v_exp_f32_e32 v39, v39
	v_sub_f32_e32 v35, v35, v38
	v_add_f32_e32 v38, 1.0, v39
	v_min_f32_e32 v36, 0, v36
	v_fma_f32 v34, v34, s93, 0
	v_log_f32_e32 v38, v38
	v_fmamk_f32 v35, v35, 0x3db8aa3b, v34
	v_mul_f32_e32 v39, 0x3f317217, v38
	v_fma_f32 v39, v38, s91, -v39
	v_fmac_f32_e32 v39, 0x3377d1cf, v38
	v_fmac_f32_e32 v39, 0x3f317217, v38
	s_nop 1
	v_mov_b32_e32 v38, v39
	v_mul_f32_e64 v39, |v37|, s89
	v_exp_f32_e32 v39, v39
	v_sub_f32_e32 v36, v36, v38
	v_add_f32_e32 v38, 1.0, v39
	v_min_f32_e32 v37, 0, v37
	v_fmamk_f32 v36, v36, 0x3db8aa3b, v35
	v_log_f32_e32 v38, v38
	s_waitcnt lgkmcnt(2)
	v_add_f32_e32 v40, 0, v33
	v_mul_f32_e32 v39, 0x3f317217, v38
	v_fma_f32 v39, v38, s91, -v39
	v_fmac_f32_e32 v39, 0x3377d1cf, v38
	v_fmac_f32_e32 v39, 0x3f317217, v38
	s_nop 1
	v_sub_f32_e32 v37, v37, v39
	v_fmamk_f32 v37, v37, 0x3db8aa3b, v36
	ds_bpermute_b32 v38, v83, v37
	s_waitcnt lgkmcnt(0)
	v_cndmask_b32_e64 v38, v38, 0, s[8:9]
	v_add_f32_e32 v38, v38, v37
	ds_bpermute_b32 v39, v84, v38
	s_waitcnt lgkmcnt(0)
	v_cndmask_b32_e64 v33, 0, v39, s[10:11]
	v_add_f32_e32 v33, v33, v38
	v_sub_f32_e32 v38, v33, v37
	ds_bpermute_b32 v41, v85, v33
	v_add_f32_e32 v38, v40, v38
	v_add_f32_e32 v33, v34, v38
	v_add_f32_e32 v34, v35, v38
	v_add_u32_e32 v35, 0xa800, v98
	ds_write2_b32 v35, v33, v34 offset0:64 offset1:196
	v_add_f32_e32 v33, v36, v38
	v_add_f32_e32 v34, v37, v38
	v_add_u32_e32 v35, 0xac00, v98
	ds_write2_b32 v35, v33, v34 offset0:72 offset1:204
	v_mov_b32_e32 v116, 0
	v_mov_b32_e32 v117, 0
	v_mov_b32_e32 v118, 0
	v_mov_b32_e32 v119, 0
	v_mov_b32_e32 v120, 0
	v_mov_b32_e32 v121, 0
	v_mov_b32_e32 v122, 0
	v_mov_b32_e32 v123, 0
	s_and_saveexec_b64 s[36:37], s[6:7]
	s_cbranch_execz .LBB0_490
; #define LAS __attribute__((address_space(3)))
; __device__ __forceinline__ void phase_gla_pre(const Params& P, LAS unsigned char* lds, bool dry) {
;     ...
;         for (int tt = 0; tt < 4; ++tt) {
;             bf16x8 ahi = (bf16x8){0, 0, 0, 0, 0, 0, 0, 0}, alo = ahi;
;             if (g < 2) { const f32x4 l0 = *(const LAS f32x4*)(Llr + (16 * tt + fr) * 16 + 8 * g), l1 = *(const LAS f32x4*)(Llr + (16 * tt + fr) * 16 + 8 * g + 4); split8(l0, l1, ahi, alo); }
;             f32x4 acc = (f32x4){bg, bg, bg, bg};
;             acc = __builtin_amdgcn_mfma_f32_16x16x32_bf16(alo, bhi, acc, 0, 0, 0); acc = __builtin_amdgcn_mfma_f32_16x16x32_bf16(ahi, blo, acc, 0, 0, 0); acc = __builtin_amdgcn_mfma_f32_16x16x32_bf16(ahi, bhi, acc, 0, 0, 0);
;             float pr[4];
; #pragma unroll
;             for (int r = 0; r < 4; ++r) { const float lg = acc[r]; const float ls = fminf(lg, 0.f) - __logf(1.0f + __expf(-fabsf(lg))); pr[r] = ls * (1.0f / 16.0f) + (r ? pr[r - 1] : 0.f); }
;             const float T = pr[3];
;             const float u1 = __shfl_up(T, 16), s1 = T + (g >= 1 ? u1 : 0.f);
;             const float u2 = __shfl_up(s1, 32), s2 = s1 + (g >= 2 ? u2 : 0.f);
;             const float base = run + (s2 - T); run += __shfl(s2, 48 + fr);
; #pragma unroll
;             for (int r = 0; r < 4; ++r) *(LAS float*)(Lb + (16 * tt + 4 * g + r) * BP + (16 * w + fr) * 4) = base + pr[r];
	ds_read_b128 v[32:35], v96 offset:2048
	ds_read_b128 v[36:39], v96 offset:2064
	s_waitcnt lgkmcnt(1)
	v_cvt_pk_bf16_f32 v120, v32, v33
	v_lshlrev_b32_e32 v132, 16, v120
	v_and_b32_e32 v133, 0xffff0000, v120
	v_pk_add_f32 v[32:33], v[32:33], v[132:133] neg_lo:[0,1] neg_hi:[0,1]
	v_cvt_pk_bf16_f32 v121, v34, v35
	v_lshlrev_b32_e32 v134, 16, v121
	v_and_b32_e32 v135, 0xffff0000, v121
	v_pk_add_f32 v[34:35], v[34:35], v[134:135] neg_lo:[0,1] neg_hi:[0,1]
	s_waitcnt lgkmcnt(0)
	v_cvt_pk_bf16_f32 v122, v36, v37
	v_lshlrev_b32_e32 v136, 16, v122
	v_and_b32_e32 v137, 0xffff0000, v122
	v_pk_add_f32 v[36:37], v[36:37], v[136:137] neg_lo:[0,1] neg_hi:[0,1]
	v_cvt_pk_bf16_f32 v123, v38, v39
	v_lshlrev_b32_e32 v138, 16, v123
	v_and_b32_e32 v139, 0xffff0000, v123
	v_pk_add_f32 v[38:39], v[38:39], v[138:139] neg_lo:[0,1] neg_hi:[0,1]
	s_nop 0
	v_cvt_pk_bf16_f32 v119, v38, v39
	v_cvt_pk_bf16_f32 v118, v36, v37
	v_cvt_pk_bf16_f32 v117, v34, v35
	v_cvt_pk_bf16_f32 v116, v32, v33
.LBB0_490:
	s_or_b64 exec, exec, s[36:37]
	s_nop 0
	v_mfma_f32_16x16x32_bf16 v[32:35], v[116:119], v[20:23], v[28:31]
	s_waitcnt lgkmcnt(2)
	v_add_f32_e32 v40, v40, v41
	v_mfma_f32_16x16x32_bf16 v[32:35], v[120:123], v[24:27], v[32:35]
	v_mfma_f32_16x16x32_bf16 v[32:35], v[120:123], v[20:23], v[32:35]
	s_nop 7
	v_min_f32_e32 v36, 0, v32
	v_mul_f32_e64 v32, |v32|, s89
	v_exp_f32_e32 v32, v32
	v_mul_f32_e64 v37, |v33|, s89
	v_exp_f32_e32 v37, v37
	v_add_f32_e32 v32, 1.0, v32
	v_add_f32_e32 v37, 1.0, v37
	v_log_f32_e32 v32, v32
	v_log_f32_e32 v37, v37
	v_mul_f32_e32 v39, 0x3f317217, v32
	v_fma_f32 v39, v32, s91, -v39
	v_fmac_f32_e32 v39, 0x3377d1cf, v32
	v_fmac_f32_e32 v39, 0x3f317217, v32
	v_mul_f32_e32 v42, 0x3f317217, v37
	v_sub_f32_e32 v32, v36, v39
	v_fma_f32 v36, v37, s91, -v42
	v_fmac_f32_e32 v36, 0x3377d1cf, v37
	v_fmac_f32_e32 v36, 0x3f317217, v37
	v_min_f32_e32 v33, 0, v33
	v_mul_f32_e64 v37, |v34|, s89
	v_exp_f32_e32 v37, v37
	v_sub_f32_e32 v33, v33, v36
	v_add_f32_e32 v36, 1.0, v37
	v_min_f32_e32 v34, 0, v34
	v_fma_f32 v32, v32, s93, 0
	v_log_f32_e32 v36, v36
	v_fmamk_f32 v33, v33, 0x3db8aa3b, v32
	v_mul_f32_e32 v37, 0x3f317217, v36
	v_fma_f32 v37, v36, s91, -v37
	v_fmac_f32_e32 v37, 0x3377d1cf, v36
	v_fmac_f32_e32 v37, 0x3f317217, v36
	s_nop 1
	v_mov_b32_e32 v36, v37
	v_mul_f32_e64 v37, |v35|, s89
	v_exp_f32_e32 v37, v37
	v_sub_f32_e32 v34, v34, v36
	v_add_f32_e32 v36, 1.0, v37
	v_min_f32_e32 v35, 0, v35
	v_fmamk_f32 v34, v34, 0x3db8aa3b, v33
	v_log_f32_e32 v36, v36
	s_nop 0
	v_mul_f32_e32 v37, 0x3f317217, v36
	v_fma_f32 v37, v36, s91, -v37
	v_fmac_f32_e32 v37, 0x3377d1cf, v36
	v_fmac_f32_e32 v37, 0x3f317217, v36
	s_nop 1
	v_sub_f32_e32 v35, v35, v37
	v_fmamk_f32 v35, v35, 0x3db8aa3b, v34
	ds_bpermute_b32 v36, v83, v35
	s_waitcnt lgkmcnt(0)
	v_cndmask_b32_e64 v36, v36, 0, s[8:9]
	v_add_f32_e32 v36, v36, v35
	ds_bpermute_b32 v37, v84, v36
	s_waitcnt lgkmcnt(0)
	v_cndmask_b32_e64 v37, 0, v37, s[10:11]
	v_add_f32_e32 v36, v37, v36
	v_sub_f32_e32 v37, v36, v35
	ds_bpermute_b32 v41, v85, v36
	v_add_f32_e32 v37, v40, v37
	v_add_f32_e32 v32, v32, v37
	v_add_f32_e32 v33, v33, v37
	v_add_u32_e32 v36, 0xca00, v98
	ds_write2_b32 v36, v32, v33 offset1:132
	v_add_f32_e32 v32, v34, v37
	v_add_f32_e32 v33, v35, v37
	v_add_u32_e32 v34, 0xce00, v98
	ds_write2_b32 v34, v32, v33 offset0:8 offset1:140
	v_mov_b32_e32 v124, 0
	v_mov_b32_e32 v125, 0
	v_mov_b32_e32 v126, 0
	v_mov_b32_e32 v127, 0
	v_mov_b32_e32 v128, 0
	v_mov_b32_e32 v129, 0
	v_mov_b32_e32 v130, 0
	v_mov_b32_e32 v131, 0
	s_and_saveexec_b64 s[36:37], s[6:7]
	s_cbranch_execz .LBB0_492
	ds_read_b128 v[32:35], v96 offset:3072
	ds_read_b128 v[36:39], v96 offset:3088
	s_waitcnt lgkmcnt(1)
	v_cvt_pk_bf16_f32 v128, v32, v33
	v_lshlrev_b32_e32 v132, 16, v128
	v_and_b32_e32 v133, 0xffff0000, v128
	v_pk_add_f32 v[32:33], v[32:33], v[132:133] neg_lo:[0,1] neg_hi:[0,1]
	v_cvt_pk_bf16_f32 v129, v34, v35
	v_lshlrev_b32_e32 v134, 16, v129
	v_and_b32_e32 v135, 0xffff0000, v129
	v_pk_add_f32 v[34:35], v[34:35], v[134:135] neg_lo:[0,1] neg_hi:[0,1]
	s_waitcnt lgkmcnt(0)
	v_cvt_pk_bf16_f32 v130, v36, v37
	v_lshlrev_b32_e32 v136, 16, v130
	v_and_b32_e32 v137, 0xffff0000, v130
	v_pk_add_f32 v[36:37], v[36:37], v[136:137] neg_lo:[0,1] neg_hi:[0,1]
	v_cvt_pk_bf16_f32 v131, v38, v39
	v_lshlrev_b32_e32 v138, 16, v131
	v_and_b32_e32 v139, 0xffff0000, v131
	v_pk_add_f32 v[38:39], v[38:39], v[138:139] neg_lo:[0,1] neg_hi:[0,1]
	s_nop 0
	v_cvt_pk_bf16_f32 v127, v38, v39
	v_cvt_pk_bf16_f32 v126, v36, v37
	v_cvt_pk_bf16_f32 v125, v34, v35
	v_cvt_pk_bf16_f32 v124, v32, v33
; #define LAS __attribute__((address_space(3)))
; __device__ __forceinline__ float bflo(unsigned w) { return __uint_as_float(w << 16); }
; __device__ __forceinline__ float bfhi(unsigned w) { return __uint_as_float(w & 0xffff0000u); }
; __device__ __forceinline__ void phase_gla_pre(const Params& P, LAS unsigned char* lds, bool dry) {
;     ...
;             for (int r = 0; r < 4; ++r) { const float lg = acc[r]; const float ls = fminf(lg, 0.f) - __logf(1.0f + __expf(-fabsf(lg))); pr[r] = ls * (1.0f / 16.0f) + (r ? pr[r - 1] : 0.f); }
;             const float T = pr[3];
;             const float u1 = __shfl_up(T, 16), s1 = T + (g >= 1 ? u1 : 0.f);
;             const float u2 = __shfl_up(s1, 32), s2 = s1 + (g >= 2 ? u2 : 0.f);
;             const float base = run + (s2 - T); run += __shfl(s2, 48 + fr);
; #pragma unroll
;             for (int r = 0; r < 4; ++r) *(LAS float*)(Lb + (16 * tt + 4 * g + r) * BP + (16 * w + fr) * 4) = base + pr[r];
;         }
;         __syncthreads();
;         {
;             f32x4 bb[4], bm[4], bl[4];
; #pragma unroll
;             for (int i = 0; i < 4; ++i) { bb[i] = *(const LAS f32x4*)(Lb + te * BP + (16 * kc + 4 * i) * 4); bm[i] = *(const LAS f32x4*)(Lb + 31 * BP + (16 * kc + 4 * i) * 4); bl[i] = *(const LAS f32x4*)(Lb + 63 * BP + (16 * kc + 4 * i) * 4); }
;             unsigned oqi[8], oki[8], oqd[8], oks[8];
; #pragma unroll
;             for (int e2 = 0; e2 < 8; ++e2) {
;                 const unsigned qw = e2 < 4 ? rq[0][e2] : rq[1][e2 - 4], kw = e2 < 4 ? rk[0][e2] : rk[1][e2 - 4];
;                 float vqi[2], vki[2], vqd[2], vks[2];
; #pragma unroll
;                 for (int hh = 0; hh < 2; ++hh) {
;                     const int e = 2 * e2 + hh; const float bv = bb[e >> 2][e & 3], bmv = bm[e >> 2][e & 3], blv = bl[e >> 2][e & 3];
;                     const float qv = hh ? bfhi(qw) : bflo(qw), kv = hh ? bfhi(kw) : bflo(kw);
;                     const float e1 = __expf(bv - bmv);
;                     vqi[hh] = qv * e1; vki[hh] = kv * __builtin_amdgcn_rcpf(e1); vqd[hh] = qv * __expf(bv); vks[hh] = kv * __expf(blv - bv);
;                 }
.LBB0_492:
	s_or_b64 exec, exec, s[36:37]
	s_nop 0
	v_mfma_f32_16x16x32_bf16 v[28:31], v[124:127], v[20:23], v[28:31]
	v_and_b32_e32 v111, 0xffff0000, v5
	v_and_b32_e32 v110, 0xffff0000, v4
	v_and_b32_e32 v117, 0xffff0000, v13
	v_mfma_f32_16x16x32_bf16 v[24:27], v[128:131], v[24:27], v[28:31]
	v_and_b32_e32 v116, 0xffff0000, v12
	v_and_b32_e32 v121, 0xffff0000, v7
	v_and_b32_e32 v120, 0xffff0000, v6
	v_mfma_f32_16x16x32_bf16 v[20:23], v[128:131], v[20:23], v[24:27]
	v_and_b32_e32 v127, 0xffff0000, v17
	v_and_b32_e32 v126, 0xffff0000, v16
	v_lshlrev_b32_e32 v125, 16, v17
	v_lshlrev_b32_e32 v124, 16, v16
	v_lshlrev_b32_e32 v133, 16, v11
	s_nop 2
	v_min_f32_e32 v24, 0, v20
	v_mul_f32_e64 v20, |v20|, s89
	v_exp_f32_e32 v20, v20
	v_mul_f32_e64 v25, |v21|, s89
	v_exp_f32_e32 v25, v25
	v_add_f32_e32 v20, 1.0, v20
	v_add_f32_e32 v25, 1.0, v25
	v_log_f32_e32 v20, v20
	v_log_f32_e32 v25, v25
	v_mul_f32_e32 v27, 0x3f317217, v20
	v_fma_f32 v27, v20, s91, -v27
	v_fmac_f32_e32 v27, 0x3377d1cf, v20
	v_fmac_f32_e32 v27, 0x3f317217, v20
	v_mul_f32_e32 v28, 0x3f317217, v25
	v_sub_f32_e32 v20, v24, v27
	v_fma_f32 v24, v25, s91, -v28
	v_fmac_f32_e32 v24, 0x3377d1cf, v25
	v_fmac_f32_e32 v24, 0x3f317217, v25
	v_min_f32_e32 v21, 0, v21
	v_mul_f32_e64 v25, |v22|, s89
	v_exp_f32_e32 v25, v25
	v_sub_f32_e32 v21, v21, v24
	v_add_f32_e32 v24, 1.0, v25
	v_min_f32_e32 v22, 0, v22
	v_fma_f32 v20, v20, s93, 0
	v_log_f32_e32 v24, v24
	v_fmamk_f32 v21, v21, 0x3db8aa3b, v20
	v_lshlrev_b32_e32 v132, 16, v10
	v_mul_f32_e32 v25, 0x3f317217, v24
	v_fma_f32 v25, v24, s91, -v25
	v_fmac_f32_e32 v25, 0x3377d1cf, v24
	v_fmac_f32_e32 v25, 0x3f317217, v24
	v_and_b32_e32 v135, 0xffff0000, v11
	v_and_b32_e32 v134, 0xffff0000, v10
	v_mov_b32_e32 v24, v25
	v_mul_f32_e64 v25, |v23|, s89
	v_exp_f32_e32 v25, v25
	v_sub_f32_e32 v22, v22, v24
	v_add_f32_e32 v24, 1.0, v25
	v_min_f32_e32 v23, 0, v23
	v_fmamk_f32 v22, v22, 0x3db8aa3b, v21
	v_log_f32_e32 v24, v24
	s_waitcnt lgkmcnt(2)
	v_add_f32_e32 v26, v40, v41
	s_and_b32 s74, s1, 0xfc0
	s_ashr_i32 s83, s82, 31
	v_mul_f32_e32 v25, 0x3f317217, v24
	v_fma_f32 v25, v24, s91, -v25
	v_fmac_f32_e32 v25, 0x3377d1cf, v24
	v_fmac_f32_e32 v25, 0x3f317217, v24
	s_nop 1
	v_sub_f32_e32 v23, v23, v25
	v_fmamk_f32 v23, v23, 0x3db8aa3b, v22
	ds_bpermute_b32 v24, v83, v23
	s_lshl_b64 s[36:37], s[82:83], 20
	s_waitcnt lgkmcnt(0)
	v_cndmask_b32_e64 v24, v24, 0, s[8:9]
	v_add_f32_e32 v24, v24, v23
	ds_bpermute_b32 v25, v84, v24
	s_waitcnt lgkmcnt(0)
	v_cndmask_b32_e64 v25, 0, v25, s[10:11]
	v_add_f32_e32 v24, v25, v24
	v_sub_f32_e32 v24, v24, v23
	v_add_f32_e32 v24, v26, v24
	v_add_f32_e32 v20, v20, v24
	v_add_f32_e32 v21, v21, v24
	v_add_u32_e32 v25, 0xea00, v98
	ds_write2_b32 v25, v20, v21 offset0:64 offset1:196
	v_add_f32_e32 v20, v22, v24
	v_add_f32_e32 v21, v23, v24
	v_add_u32_e32 v22, 0xee00, v98
	ds_write2_b32 v22, v20, v21 offset0:72 offset1:204
	v_add_u32_e32 v22, s94, v87
	s_waitcnt lgkmcnt(0)
	s_barrier
	v_add_u32_e32 v20, v86, v87
	v_add_u32_e32 v21, 0, v87
	ds_read_b128 v[32:35], v22
	ds_read_b128 v[24:27], v89
	ds_read_b128 v[60:63], v21 offset:51184
	ds_read_b128 v[64:67], v20 offset:34816
	ds_read_b128 v[74:77], v20 offset:34832
	ds_read_b128 v[44:47], v20 offset:34848
	ds_read_b128 v[36:39], v20 offset:34864
	ds_read_b128 v[100:103], v21 offset:51200
	s_waitcnt lgkmcnt(4)
	v_sub_f32_e32 v61, v65, v61
	v_sub_f32_e32 v63, v67, v63
	v_exp_f32_e32 v72, v61
	v_sub_f32_e32 v61, v32, v64
	v_exp_f32_e32 v73, v63
	v_exp_f32_e32 v78, v61
	v_sub_f32_e32 v20, v64, v60
	v_exp_f32_e32 v108, v65
	v_sub_f32_e32 v61, v66, v62
	v_sub_f32_e32 v62, v33, v65
	v_sub_f32_e32 v63, v34, v66
	v_exp_f32_e32 v60, v20
	v_exp_f32_e32 v70, v64
	v_rcp_f32_e32 v64, v72
	v_exp_f32_e32 v61, v61
	v_exp_f32_e32 v71, v66
	v_rcp_f32_e32 v65, v73
	v_exp_f32_e32 v79, v63
	v_exp_f32_e32 v109, v67
	v_sub_f32_e32 v63, v35, v67
	v_lshlrev_b32_e32 v67, 16, v5
	v_lshlrev_b32_e32 v66, 16, v4
	v_pk_mul_f32 v[112:113], v[60:61], v[66:67]
	v_pk_mul_f32 v[114:115], v[72:73], v[110:111]
	v_pk_mul_f32 v[72:73], v[64:65], v[116:117]
	v_pk_mul_f32 v[64:65], v[70:71], v[66:67]
	s_waitcnt lgkmcnt(0)
	v_sub_f32_e32 v66, v74, v100
	v_exp_f32_e32 v70, v66
	v_pk_mul_f32 v[66:67], v[108:109], v[110:111]
	v_exp_f32_e32 v108, v74
	v_sub_f32_e32 v71, v75, v101
	v_exp_f32_e32 v100, v71
	v_sub_f32_e32 v71, v24, v74
	v_exp_f32_e32 v62, v62
	v_exp_f32_e32 v63, v63
	v_exp_f32_e32 v74, v71
	v_mov_b32_e32 v71, v75
	v_sub_f32_e32 v75, v25, v75
	v_exp_f32_e32 v118, v75
	v_pk_mul_f32 v[62:63], v[62:63], v[116:117]
	v_exp_f32_e32 v116, v71
	v_sub_f32_e32 v71, v76, v102
	v_exp_f32_e32 v109, v76
	v_sub_f32_e32 v75, v77, v103
	v_rcp_f32_e32 v68, v60
	v_rcp_f32_e32 v69, v61
	v_exp_f32_e32 v71, v71
	v_exp_f32_e32 v101, v75
	v_sub_f32_e32 v75, v26, v76
	v_exp_f32_e32 v117, v77
	v_sub_f32_e32 v76, v27, v77
	v_lshlrev_b32_e32 v61, 16, v13
	v_lshlrev_b32_e32 v60, 16, v12
	v_exp_f32_e32 v119, v76
	v_lshlrev_b32_e32 v77, 16, v7
	v_lshlrev_b32_e32 v76, 16, v6
	v_pk_mul_f32 v[68:69], v[68:69], v[60:61]
	v_pk_mul_f32 v[60:61], v[78:79], v[60:61]
	v_rcp_f32_e32 v78, v70
	v_rcp_f32_e32 v110, v100
	v_rcp_f32_e32 v79, v71
	v_rcp_f32_e32 v111, v101
	v_pk_mul_f32 v[70:71], v[70:71], v[76:77]
	v_pk_mul_f32 v[100:101], v[100:101], v[120:121]
	v_cvt_pk_bf16_f32 v224, v112, v114
	v_cvt_pk_bf16_f32 v222, v113, v115
	v_cvt_pk_bf16_f32 v102, v70, v100
	v_cvt_pk_bf16_f32 v103, v71, v101
	ds_read_b128 v[104:107], v21 offset:51216
	ds_read_b128 v[40:43], v21 offset:51232
	ds_read_b128 v[28:31], v90
	ds_read_b128 v[20:23], v91
	v_lshlrev_b32_e32 v71, 16, v15
	v_lshlrev_b32_e32 v70, 16, v14
	v_mov_b32_e32 v101, v222
	v_mov_b32_e32 v100, v224
	v_pk_mul_f32 v[114:115], v[78:79], v[70:71]
	s_waitcnt lgkmcnt(3)
; #define LAS __attribute__((address_space(3)))
; __device__ __forceinline__ float bflo(unsigned w) { return __uint_as_float(w << 16); }
; __device__ __forceinline__ float bfhi(unsigned w) { return __uint_as_float(w & 0xffff0000u); }
; __device__ __forceinline__ unsigned pk2(float lo, float hi) { return f2bf(lo) | (f2bf(hi) << 16); }
; __device__ __forceinline__ void phase_gla_pre(const Params& P, LAS unsigned char* lds, bool dry) {
;     ...
;             for (int e2 = 0; e2 < 8; ++e2) {
;                 const unsigned qw = e2 < 4 ? rq[0][e2] : rq[1][e2 - 4], kw = e2 < 4 ? rk[0][e2] : rk[1][e2 - 4];
;                 float vqi[2], vki[2], vqd[2], vks[2];
; #pragma unroll
;                 for (int hh = 0; hh < 2; ++hh) {
;                     const int e = 2 * e2 + hh; const float bv = bb[e >> 2][e & 3], bmv = bm[e >> 2][e & 3], blv = bl[e >> 2][e & 3];
;                     const float qv = hh ? bfhi(qw) : bflo(qw), kv = hh ? bfhi(kw) : bflo(kw);
;                     const float e1 = __expf(bv - bmv);
;                     vqi[hh] = qv * e1; vki[hh] = kv * __builtin_amdgcn_rcpf(e1); vqd[hh] = qv * __expf(bv); vks[hh] = kv * __expf(blv - bv);
;                 }
;                 oqi[e2] = pk2(vqi[0], vqi[1]); oki[e2] = pk2(vki[0], vki[1]); oqd[e2] = pk2(vqd[0], vqd[1]); oks[e2] = pk2(vks[0], vks[1]);
;             }
;             *(LAS u32x4*)(Lqi + te * QP + 32 * kc) = (u32x4){oqi[0], oqi[1], oqi[2], oqi[3]}; *(LAS u32x4*)(Lqi + te * QP + 32 * kc + 16) = (u32x4){oqi[4], oqi[5], oqi[6], oqi[7]};
;             *(LAS u32x4*)(Lki + te * QP + 32 * kc) = (u32x4){oki[0], oki[1], oki[2], oki[3]}; *(LAS u32x4*)(Lki + te * QP + 32 * kc + 16) = (u32x4){oki[4], oki[5], oki[6], oki[7]};
;             if (!dry) {
;                 bf16_t* p_ = PJ + ((size_t)bh * SEQ + c * 64 + te) * 128 + 16 * kc;
;                 *(u32x4*)(p_ + T_Q) = (u32x4){oqd[0], oqd[1], oqd[2], oqd[3]}; *(u32x4*)(p_ + T_Q + 8) = (u32x4){oqd[4], oqd[5], oqd[6], oqd[7]};
;                 *(u32x4*)(p_ + T_K) = (u32x4){oks[0], oks[1], oks[2], oks[3]}; *(u32x4*)(p_ + T_K + 8) = (u32x4){oks[4], oks[5], oks[6], oks[7]};
;                 if (te == 63) {
; #pragma unroll
;                     for (int i = 0; i < 4; ++i) *(f32x4*)(DEC + (size_t)item * 128 + 16 * kc + 4 * i) = (f32x4){__expf(bl[i][0]), __expf(bl[i][1]), __expf(bl[i][2]), __expf(bl[i][3])};
;                 }
	v_sub_f32_e32 v78, v44, v104
	v_sub_f32_e32 v105, v45, v105
	v_exp_f32_e32 v75, v75
	v_exp_f32_e32 v104, v78
	v_pk_mul_f32 v[78:79], v[116:117], v[120:121]
	v_exp_f32_e32 v116, v105
	v_mov_b32_e32 v105, v45
	s_waitcnt lgkmcnt(1)
	v_sub_f32_e32 v45, v29, v45
	v_and_b32_e32 v113, 0xffff0000, v15
	v_and_b32_e32 v112, 0xffff0000, v14
	v_exp_f32_e32 v120, v105
	v_sub_f32_e32 v105, v46, v106
	v_exp_f32_e32 v106, v45
	v_pk_mul_f32 v[110:111], v[110:111], v[112:113]
	v_pk_mul_f32 v[70:71], v[74:75], v[70:71]
	v_pk_mul_f32 v[74:75], v[118:119], v[112:113]
	v_exp_f32_e32 v113, v46
	v_sub_f32_e32 v45, v47, v107
	v_exp_f32_e32 v117, v45
	v_sub_f32_e32 v45, v30, v46
	v_exp_f32_e32 v121, v47
	v_sub_f32_e32 v46, v31, v47
	v_pk_mul_f32 v[76:77], v[108:109], v[76:77]
	v_exp_f32_e32 v112, v44
	v_exp_f32_e32 v105, v105
	v_exp_f32_e32 v107, v46
	v_rcp_f32_e32 v118, v116
	v_rcp_f32_e32 v119, v117
	v_sub_f32_e32 v44, v28, v44
	v_lshlrev_b32_e32 v47, 16, v9
	v_lshlrev_b32_e32 v46, 16, v8
	v_rcp_f32_e32 v108, v104
	v_rcp_f32_e32 v109, v105
	v_pk_mul_f32 v[104:105], v[104:105], v[46:47]
	v_pk_mul_f32 v[112:113], v[112:113], v[46:47]
	v_sub_f32_e32 v40, v36, v40
	v_pk_mul_f32 v[46:47], v[106:107], v[126:127]
	v_mov_b32_e32 v107, v36
	s_waitcnt lgkmcnt(0)
	v_sub_f32_e32 v36, v20, v36
	v_exp_f32_e32 v44, v44
	v_exp_f32_e32 v45, v45
	v_pk_mul_f32 v[118:119], v[118:119], v[126:127]
	v_exp_f32_e32 v126, v36
	v_sub_f32_e32 v41, v37, v41
	v_exp_f32_e32 v130, v37
	v_sub_f32_e32 v36, v38, v42
	v_pk_mul_f32 v[108:109], v[108:109], v[124:125]
	v_pk_mul_f32 v[44:45], v[44:45], v[124:125]
	v_exp_f32_e32 v124, v41
	v_exp_f32_e32 v41, v36
	v_sub_f32_e32 v36, v21, v37
	v_and_b32_e32 v123, 0xffff0000, v9
	v_and_b32_e32 v122, 0xffff0000, v8
	v_exp_f32_e32 v42, v36
	v_pk_mul_f32 v[116:117], v[116:117], v[122:123]
	v_pk_mul_f32 v[120:121], v[120:121], v[122:123]
	v_exp_f32_e32 v123, v38
	v_sub_f32_e32 v36, v39, v43
	v_exp_f32_e32 v125, v36
	v_sub_f32_e32 v36, v22, v38
	v_exp_f32_e32 v40, v40
	v_exp_f32_e32 v127, v36
	v_exp_f32_e32 v131, v39
	v_sub_f32_e32 v36, v23, v39
	v_rcp_f32_e32 v128, v124
	v_rcp_f32_e32 v129, v125
	v_exp_f32_e32 v43, v36
	v_pk_mul_f32 v[36:37], v[40:41], v[132:133]
	v_pk_mul_f32 v[38:39], v[124:125], v[134:135]
	v_rcp_f32_e32 v106, v40
	v_exp_f32_e32 v122, v107
	v_rcp_f32_e32 v107, v41
	v_cvt_pk_bf16_f32 v228, v104, v116
	v_cvt_pk_bf16_f32 v227, v105, v117
	v_cvt_pk_bf16_f32 v38, v36, v38
	v_cvt_pk_bf16_f32 v39, v37, v39
	v_mov_b32_e32 v37, v227
	v_mov_b32_e32 v36, v228
	ds_write_b128 v92, v[100:103]
	ds_write_b128 v92, v[36:39] offset:16
	v_cvt_pk_bf16_f32 v36, v68, v72
	v_cvt_pk_bf16_f32 v37, v69, v73
	v_lshlrev_b32_e32 v41, 16, v19
	v_lshlrev_b32_e32 v40, 16, v18
	v_cvt_pk_bf16_f32 v39, v115, v111
	v_cvt_pk_bf16_f32 v38, v114, v110
	v_and_b32_e32 v105, 0xffff0000, v19
	v_and_b32_e32 v104, 0xffff0000, v18
	v_pk_mul_f32 v[106:107], v[106:107], v[40:41]
	ds_write_b128 v92, v[36:39] offset:17408
	v_pk_mul_f32 v[116:117], v[128:129], v[104:105]
	s_nop 0
	v_cvt_pk_bf16_f32 v39, v107, v117
	v_cvt_pk_bf16_f32 v38, v106, v116
	v_cvt_pk_bf16_f32 v37, v109, v119
	v_cvt_pk_bf16_f32 v36, v108, v118
	ds_write_b128 v92, v[36:39] offset:17424
	v_lshl_add_u64 v[36:37], s[74:75], 0, v[48:49]
	v_lshlrev_b64 v[36:37], 8, v[36:37]
	v_lshl_add_u64 v[38:39], v[52:53], 0, s[36:37]
	v_lshl_add_u64 v[68:69], v[38:39], 0, v[36:37]
	v_cvt_pk_bf16_f32 v36, v64, v66
	v_cvt_pk_bf16_f32 v37, v65, v67
	s_brev_b32 s36, 16
	v_cvt_pk_bf16_f32 v39, v77, v79
	v_add_co_u32_e32 v64, vcc, s36, v68
	v_cvt_pk_bf16_f32 v38, v76, v78
	s_nop 0
	v_addc_co_u32_e32 v65, vcc, 0, v69, vcc
	v_pk_mul_f32 v[122:123], v[122:123], v[132:133]
	global_store_dwordx4 v[64:65], v[36:39], off
	v_pk_mul_f32 v[124:125], v[130:131], v[134:135]
	s_nop 0
	v_cvt_pk_bf16_f32 v39, v123, v125
	v_cvt_pk_bf16_f32 v38, v122, v124
	v_cvt_pk_bf16_f32 v37, v113, v121
	v_cvt_pk_bf16_f32 v36, v112, v120
	global_store_dwordx4 v[64:65], v[36:39], off offset:16
	s_nop 1
	s_nop 0
	v_cvt_pk_bf16_f32 v36, v60, v62
	v_cvt_pk_bf16_f32 v37, v61, v63
	v_cvt_pk_bf16_f32 v39, v71, v75
	v_add_co_u32_e32 v60, vcc, s95, v68
	v_pk_mul_f32 v[42:43], v[42:43], v[104:105]
	v_cvt_pk_bf16_f32 v38, v70, v74
	v_addc_co_u32_e32 v61, vcc, 0, v69, vcc
	v_pk_mul_f32 v[40:41], v[126:127], v[40:41]
	global_store_dwordx4 v[60:61], v[36:39], off
	s_nop 1
	v_cvt_pk_bf16_f32 v36, v44, v46
	v_cvt_pk_bf16_f32 v37, v45, v47
	v_cvt_pk_bf16_f32 v38, v40, v42
	v_cvt_pk_bf16_f32 v39, v41, v43
	global_store_dwordx4 v[60:61], v[36:39], off offset:16
	s_and_saveexec_b64 s[36:37], s[12:13]
	s_cbranch_execz .LBB0_494
	v_exp_f32_e32 v32, v32
	v_exp_f32_e32 v33, v33
	v_exp_f32_e32 v34, v34
	v_exp_f32_e32 v35, v35
	s_ashr_i32 s81, s80, 31
	v_exp_f32_e32 v24, v24
	v_exp_f32_e32 v25, v25
	v_exp_f32_e32 v26, v26
	v_exp_f32_e32 v27, v27
	s_lshl_b64 s[42:43], s[80:81], 9
	v_exp_f32_e32 v28, v28
	v_exp_f32_e32 v29, v29
	v_exp_f32_e32 v30, v30
	v_exp_f32_e32 v31, v31
	v_lshl_add_u64 v[36:37], v[54:55], 0, s[42:43]
	v_exp_f32_e32 v20, v20
	v_exp_f32_e32 v21, v21
	v_exp_f32_e32 v22, v22
	v_exp_f32_e32 v23, v23
	global_store_dwordx4 v[36:37], v[32:35], off
	global_store_dwordx4 v[36:37], v[24:27], off offset:16
	global_store_dwordx4 v[36:37], v[28:31], off offset:32
	global_store_dwordx4 v[36:37], v[20:23], off offset:48
